# A pass-2 epilogue: the 16 group-norm gain quads loaded once at the epilogue top into free VGPRs instead of 8 serialized load-wait-use-store steps
# speedup vs baseline: 1.0031x; 1.0031x over previous
;     DI void* gp(int i) const { return (void*)(__attribute__((address_space(1))) void*)ld(i); }
; DI float bflo(unsigned w) { return __uint_as_float(w << 16); }
; DI float bfhi(unsigned w) { return __uint_as_float(w & 0xffff0000u); }
; template <int DQK, int MODE>
; DI void attn_body(const AttnArgs& a, char* lds) {
;     ...
;         } else {
;             float v[64]; float ss = 0.f;
; #pragma unroll
;             for (int c = 0; c < 8; ++c) { const u32x4 w2 = *(const u32x4*)(sp + c * 16); const u32x4 w1 = *(const u32x4*)(gp + c * 8);
;                 v[c * 8 + 0] = bflo(w1.x) - a.lam * bflo(w2.x); v[c * 8 + 1] = bfhi(w1.x) - a.lam * bfhi(w2.x);
;                 v[c * 8 + 2] = bflo(w1.y) - a.lam * bflo(w2.y); v[c * 8 + 3] = bfhi(w1.y) - a.lam * bfhi(w2.y);
;                 v[c * 8 + 4] = bflo(w1.z) - a.lam * bflo(w2.z); v[c * 8 + 5] = bfhi(w1.z) - a.lam * bfhi(w2.z);
;                 v[c * 8 + 6] = bflo(w1.w) - a.lam * bflo(w2.w); v[c * 8 + 7] = bfhi(w1.w) - a.lam * bfhi(w2.w); }
; #pragma unroll
;             for (int i = 0; i < 64; ++i) ss += v[i] * v[i];
.LBB0_758:
	v_lshlrev_b32_e32 v60, 6, v6
	v_lshlrev_b32_e32 v198, 8, v6
	global_load_dwordx4 v[86:89], v198, s[60:61]
	global_load_dwordx4 v[90:93], v198, s[60:61] offset:16
	global_load_dwordx4 v[94:97], v198, s[60:61] offset:32
	global_load_dwordx4 v[98:101], v198, s[60:61] offset:48
	global_load_dwordx4 v[102:105], v198, s[60:61] offset:64
	global_load_dwordx4 v[106:109], v198, s[60:61] offset:80
	global_load_dwordx4 v[110:113], v198, s[60:61] offset:96
	global_load_dwordx4 v[114:117], v198, s[60:61] offset:112
	global_load_dwordx4 v[118:121], v198, s[60:61] offset:128
	global_load_dwordx4 v[122:125], v198, s[60:61] offset:144
	global_load_dwordx4 v[126:129], v198, s[60:61] offset:160
	global_load_dwordx4 v[130:133], v198, s[60:61] offset:176
	global_load_dwordx4 v[134:137], v198, s[60:61] offset:192
	global_load_dwordx4 v[138:141], v198, s[60:61] offset:208
	global_load_dwordx4 v[142:145], v198, s[60:61] offset:224
	global_load_dwordx4 v[194:197], v198, s[60:61] offset:240
	global_load_dwordx4 v[6:9], v[26:27], off offset:48
	global_load_dwordx4 v[14:17], v[26:27], off offset:32
	global_load_dwordx4 v[18:21], v[26:27], off offset:16
	global_load_dwordx4 v[10:13], v[26:27], off
	s_waitcnt lgkmcnt(0)
	v_lshlrev_b32_e32 v23, 16, v2
	v_lshlrev_b32_e32 v60, 2, v60
	s_waitcnt vmcnt(1)
	v_lshlrev_b32_e32 v28, 16, v18
	s_waitcnt vmcnt(0)
	v_lshlrev_b32_e32 v22, 16, v10
	v_fma_f32 v29, -v148, v23, v22
	v_and_b32_e32 v10, 0xffff0000, v10
	v_and_b32_e32 v22, 0xffff0000, v2
	v_fma_f32 v31, -v148, v22, v10
	v_lshlrev_b32_e32 v10, 16, v11
	v_lshlrev_b32_e32 v22, 16, v3
	v_fma_f32 v34, -v148, v22, v10
	v_and_b32_e32 v10, 0xffff0000, v11
	v_and_b32_e32 v11, 0xffff0000, v3
	v_fma_f32 v37, -v148, v11, v10
	v_lshlrev_b32_e32 v10, 16, v12
	v_lshlrev_b32_e32 v11, 16, v4
	v_fma_f32 v39, -v148, v11, v10
	v_and_b32_e32 v10, 0xffff0000, v12
	v_and_b32_e32 v11, 0xffff0000, v4
	v_fma_f32 v41, -v148, v11, v10
	v_lshlrev_b32_e32 v10, 16, v13
	v_lshlrev_b32_e32 v11, 16, v5
	v_fma_f32 v50, -v148, v11, v10
	v_and_b32_e32 v10, 0xffff0000, v13
	v_and_b32_e32 v11, 0xffff0000, v5
	v_fma_f32 v56, -v148, v11, v10
	ds_read_b128 v[22:25], v0 offset:16
	ds_read_b128 v[46:49], v0 offset:32
	ds_read_b128 v[62:65], v0 offset:48
	ds_read_b128 v[10:13], v0 offset:64
	v_and_b32_e32 v18, 0xffff0000, v18
	s_waitcnt lgkmcnt(3)
	v_lshlrev_b32_e32 v30, 16, v22
	v_and_b32_e32 v22, 0xffff0000, v22
	v_fma_f32 v52, -v148, v22, v18
	v_lshlrev_b32_e32 v18, 16, v19
	v_lshlrev_b32_e32 v22, 16, v23
	v_fma_f32 v53, -v148, v22, v18
	v_and_b32_e32 v18, 0xffff0000, v19
	v_and_b32_e32 v19, 0xffff0000, v23
	v_fma_f32 v54, -v148, v19, v18
	v_lshlrev_b32_e32 v18, 16, v20
	v_lshlrev_b32_e32 v19, 16, v24
	v_fma_f32 v55, -v148, v19, v18
	v_and_b32_e32 v18, 0xffff0000, v20
	v_and_b32_e32 v19, 0xffff0000, v24
	v_fma_f32 v57, -v148, v19, v18
	v_lshlrev_b32_e32 v18, 16, v21
	v_lshlrev_b32_e32 v19, 16, v25
	v_fma_f32 v58, -v148, v19, v18
	v_and_b32_e32 v18, 0xffff0000, v21
	v_and_b32_e32 v19, 0xffff0000, v25
	v_fma_f32 v59, -v148, v19, v18
	v_lshlrev_b32_e32 v18, 16, v14
	s_waitcnt lgkmcnt(2)
	v_lshlrev_b32_e32 v19, 16, v46
	v_fma_f32 v42, -v148, v19, v18
	v_and_b32_e32 v14, 0xffff0000, v14
	v_and_b32_e32 v18, 0xffff0000, v46
	v_fma_f32 v43, -v148, v18, v14
	v_lshlrev_b32_e32 v14, 16, v15
	v_lshlrev_b32_e32 v18, 16, v47
	v_fma_f32 v44, -v148, v18, v14
	v_and_b32_e32 v14, 0xffff0000, v15
	v_and_b32_e32 v15, 0xffff0000, v47
	v_fma_f32 v45, -v148, v15, v14
	v_lshlrev_b32_e32 v14, 16, v16
	v_lshlrev_b32_e32 v15, 16, v48
	v_fma_f32 v46, -v148, v15, v14
	v_and_b32_e32 v14, 0xffff0000, v16
	v_and_b32_e32 v15, 0xffff0000, v48
	v_fma_f32 v47, -v148, v15, v14
	v_lshlrev_b32_e32 v14, 16, v17
	v_lshlrev_b32_e32 v15, 16, v49
	v_fma_f32 v48, -v148, v15, v14
	v_and_b32_e32 v14, 0xffff0000, v17
	v_and_b32_e32 v15, 0xffff0000, v49
	v_fma_f32 v49, -v148, v15, v14
	v_lshlrev_b32_e32 v14, 16, v6
	s_waitcnt lgkmcnt(1)
	v_lshlrev_b32_e32 v15, 16, v62
	v_fma_f32 v40, -v148, v15, v14
	v_and_b32_e32 v6, 0xffff0000, v6
	v_and_b32_e32 v14, 0xffff0000, v62
	v_fma_f32 v38, -v148, v14, v6
	v_lshlrev_b32_e32 v6, 16, v7
	v_lshlrev_b32_e32 v14, 16, v63
	v_fma_f32 v36, -v148, v14, v6
	v_and_b32_e32 v6, 0xffff0000, v7
	v_and_b32_e32 v7, 0xffff0000, v63
	v_fma_f32 v35, -v148, v7, v6
	v_lshlrev_b32_e32 v6, 16, v8
	v_lshlrev_b32_e32 v7, 16, v64
	v_fma_f32 v33, -v148, v7, v6
	v_and_b32_e32 v6, 0xffff0000, v8
	v_and_b32_e32 v7, 0xffff0000, v64
	v_fma_f32 v32, -v148, v7, v6
	v_lshlrev_b32_e32 v6, 16, v9
	v_lshlrev_b32_e32 v7, 16, v65
	v_fma_f32 v51, -v148, v30, v28
	v_fma_f32 v30, -v148, v7, v6
	v_and_b32_e32 v6, 0xffff0000, v9
	v_and_b32_e32 v7, 0xffff0000, v65
	v_fma_f32 v28, -v148, v7, v6
	global_load_dwordx4 v[6:9], v[26:27], off offset:112
	global_load_dwordx4 v[14:17], v[26:27], off offset:96
	global_load_dwordx4 v[18:21], v[26:27], off offset:80
	global_load_dwordx4 v[22:25], v[26:27], off offset:64
	s_waitcnt lgkmcnt(0)
	v_lshlrev_b32_e32 v62, 16, v10
	v_and_b32_e32 v10, 0xffff0000, v10
	ds_read_b128 v[82:85], v0 offset:112
	s_waitcnt vmcnt(0)
	v_lshlrev_b32_e32 v61, 16, v22
	v_and_b32_e32 v22, 0xffff0000, v22
	v_fma_f32 v80, -v148, v10, v22
	v_lshlrev_b32_e32 v10, 16, v23
	v_lshlrev_b32_e32 v22, 16, v11
	v_fma_f32 v79, -v148, v22, v10
	v_and_b32_e32 v10, 0xffff0000, v23
	v_and_b32_e32 v11, 0xffff0000, v11
	v_fma_f32 v78, -v148, v11, v10
	v_lshlrev_b32_e32 v10, 16, v24
	v_lshlrev_b32_e32 v11, 16, v12
	v_fma_f32 v75, -v148, v11, v10
	v_and_b32_e32 v10, 0xffff0000, v24
	v_and_b32_e32 v11, 0xffff0000, v12
	v_fma_f32 v74, -v148, v11, v10
	v_lshlrev_b32_e32 v10, 16, v25
	v_lshlrev_b32_e32 v11, 16, v13
	v_fma_f32 v71, -v148, v11, v10
	v_and_b32_e32 v10, 0xffff0000, v25
	v_and_b32_e32 v11, 0xffff0000, v13
	v_fma_f32 v70, -v148, v11, v10
	ds_read_b128 v[10:13], v0 offset:80
	v_lshlrev_b32_e32 v22, 16, v18
	v_and_b32_e32 v18, 0xffff0000, v18
	v_fma_f32 v81, -v148, v62, v61
	s_waitcnt lgkmcnt(0)
;     DI void* gp(int i) const { return (void*)(__attribute__((address_space(1))) void*)ld(i); }
; DI float bflo(unsigned w) { return __uint_as_float(w << 16); }
; DI float bfhi(unsigned w) { return __uint_as_float(w & 0xffff0000u); }
; template <int M> DI float sx(float v) { return __int_as_float(__builtin_amdgcn_ds_swizzle(__float_as_int(v), (M << 10) | 0x1f)); }
; template <int DQK, int MODE>
; DI void attn_body(const AttnArgs& a, char* lds) {
;     ...
;             for (int c = 0; c < 8; ++c) { const u32x4 w2 = *(const u32x4*)(sp + c * 16); const u32x4 w1 = *(const u32x4*)(gp + c * 8);
;                 v[c * 8 + 0] = bflo(w1.x) - a.lam * bflo(w2.x); v[c * 8 + 1] = bfhi(w1.x) - a.lam * bfhi(w2.x);
;                 v[c * 8 + 2] = bflo(w1.y) - a.lam * bflo(w2.y); v[c * 8 + 3] = bfhi(w1.y) - a.lam * bfhi(w2.y);
;                 v[c * 8 + 4] = bflo(w1.z) - a.lam * bflo(w2.z); v[c * 8 + 5] = bfhi(w1.z) - a.lam * bfhi(w2.z);
;                 v[c * 8 + 6] = bflo(w1.w) - a.lam * bflo(w2.w); v[c * 8 + 7] = bfhi(w1.w) - a.lam * bfhi(w2.w); }
; #pragma unroll
;             for (int i = 0; i < 64; ++i) ss += v[i] * v[i];
;             ss += sx<1>(ss);
	v_lshlrev_b32_e32 v23, 16, v10
	v_and_b32_e32 v10, 0xffff0000, v10
	v_fma_f32 v65, -v148, v10, v18
	v_lshlrev_b32_e32 v10, 16, v19
	v_lshlrev_b32_e32 v18, 16, v11
	v_fma_f32 v64, -v148, v18, v10
	v_and_b32_e32 v10, 0xffff0000, v19
	v_and_b32_e32 v11, 0xffff0000, v11
	v_fma_f32 v63, -v148, v11, v10
	v_lshlrev_b32_e32 v10, 16, v20
	v_lshlrev_b32_e32 v11, 16, v12
	v_fma_f32 v62, -v148, v11, v10
	v_and_b32_e32 v10, 0xffff0000, v20
	v_and_b32_e32 v11, 0xffff0000, v12
	v_fma_f32 v61, -v148, v11, v10
	v_lshlrev_b32_e32 v10, 16, v21
	v_lshlrev_b32_e32 v11, 16, v13
	v_fma_f32 v25, -v148, v11, v10
	v_and_b32_e32 v10, 0xffff0000, v21
	v_and_b32_e32 v11, 0xffff0000, v13
	v_fma_f32 v24, -v148, v11, v10
	ds_read_b128 v[10:13], v0 offset:96
	v_lshlrev_b32_e32 v18, 16, v14
	v_and_b32_e32 v14, 0xffff0000, v14
	v_fma_f32 v66, -v148, v23, v22
	s_waitcnt lgkmcnt(0)
	v_lshlrev_b32_e32 v19, 16, v10
	v_and_b32_e32 v10, 0xffff0000, v10
	v_fma_f32 v76, -v148, v10, v14
	v_lshlrev_b32_e32 v10, 16, v15
	v_lshlrev_b32_e32 v14, 16, v11
	v_fma_f32 v73, -v148, v14, v10
	v_mul_f32_e32 v14, v31, v31
	v_fmac_f32_e32 v14, v29, v29
	v_fmac_f32_e32 v14, v34, v34
	v_fmac_f32_e32 v14, v37, v37
	v_fmac_f32_e32 v14, v39, v39
	v_fmac_f32_e32 v14, v41, v41
	v_fmac_f32_e32 v14, v50, v50
	v_fmac_f32_e32 v14, v56, v56
	v_fmac_f32_e32 v14, v51, v51
	v_fmac_f32_e32 v14, v52, v52
	v_fmac_f32_e32 v14, v53, v53
	v_fmac_f32_e32 v14, v54, v54
	v_fmac_f32_e32 v14, v55, v55
	v_fmac_f32_e32 v14, v57, v57
	v_fmac_f32_e32 v14, v58, v58
	v_fmac_f32_e32 v14, v59, v59
	v_fmac_f32_e32 v14, v42, v42
	v_fmac_f32_e32 v14, v43, v43
	v_fmac_f32_e32 v14, v44, v44
	v_fmac_f32_e32 v14, v45, v45
	v_fmac_f32_e32 v14, v46, v46
	v_fmac_f32_e32 v14, v47, v47
	v_fmac_f32_e32 v14, v48, v48
	v_fmac_f32_e32 v14, v49, v49
	v_fmac_f32_e32 v14, v40, v40
	v_fmac_f32_e32 v14, v38, v38
	v_fmac_f32_e32 v14, v36, v36
	v_fmac_f32_e32 v14, v35, v35
	v_fmac_f32_e32 v14, v33, v33
	v_fmac_f32_e32 v14, v32, v32
	v_fmac_f32_e32 v14, v30, v30
	v_fmac_f32_e32 v14, v28, v28
	v_fmac_f32_e32 v14, v81, v81
	v_fmac_f32_e32 v14, v80, v80
	v_fmac_f32_e32 v14, v79, v79
	v_fmac_f32_e32 v14, v78, v78
	v_fmac_f32_e32 v14, v75, v75
	v_fmac_f32_e32 v14, v74, v74
	v_fmac_f32_e32 v14, v71, v71
	v_fmac_f32_e32 v14, v70, v70
	v_fmac_f32_e32 v14, v66, v66
	v_fmac_f32_e32 v14, v65, v65
	v_fmac_f32_e32 v14, v64, v64
	v_fmac_f32_e32 v14, v63, v63
	v_fmac_f32_e32 v14, v62, v62
	v_fmac_f32_e32 v14, v61, v61
	v_fmac_f32_e32 v14, v25, v25
	v_fma_f32 v77, -v148, v19, v18
	v_fmac_f32_e32 v14, v24, v24
	v_and_b32_e32 v10, 0xffff0000, v15
	v_and_b32_e32 v11, 0xffff0000, v11
	v_fmac_f32_e32 v14, v77, v77
	v_fma_f32 v72, -v148, v11, v10
	v_lshlrev_b32_e32 v10, 16, v16
	v_lshlrev_b32_e32 v11, 16, v12
	v_fmac_f32_e32 v14, v76, v76
	v_fma_f32 v68, -v148, v11, v10
	v_and_b32_e32 v10, 0xffff0000, v16
	v_and_b32_e32 v11, 0xffff0000, v12
	v_fmac_f32_e32 v14, v73, v73
	v_fma_f32 v67, -v148, v11, v10
	v_fmac_f32_e32 v14, v72, v72
	v_and_b32_e32 v10, 0xffff0000, v17
	v_lshlrev_b32_e32 v11, 16, v17
	v_and_b32_e32 v12, 0xffff0000, v13
	v_lshlrev_b32_e32 v13, 16, v13
	v_fmac_f32_e32 v14, v68, v68
	v_pk_fma_f32 v[22:23], v[148:149], v[12:13], v[10:11] neg_lo:[1,0,0] neg_hi:[1,0,0]
	v_fmac_f32_e32 v14, v67, v67
	v_pk_mul_f32 v[10:11], v[22:23], v[22:23]
	v_and_b32_e32 v12, 0xffff0000, v82
	v_add_f32_e32 v11, v11, v14
	v_add_f32_e32 v14, v10, v11
	v_and_b32_e32 v10, 0xffff0000, v6
	v_lshlrev_b32_e32 v11, 16, v6
	v_lshlrev_b32_e32 v13, 16, v82
	v_pk_fma_f32 v[20:21], v[148:149], v[12:13], v[10:11] neg_lo:[1,0,0] neg_hi:[1,0,0]
	s_nop 0
	v_pk_mul_f32 v[10:11], v[20:21], v[20:21]
	s_nop 0
	v_add_f32_e32 v6, v11, v14
	v_add_f32_e32 v12, v10, v6
	v_and_b32_e32 v6, 0xffff0000, v7
	v_lshlrev_b32_e32 v7, 16, v7
	v_and_b32_e32 v10, 0xffff0000, v83
	v_lshlrev_b32_e32 v11, 16, v83
	v_pk_fma_f32 v[18:19], v[148:149], v[10:11], v[6:7] neg_lo:[1,0,0] neg_hi:[1,0,0]
	v_and_b32_e32 v10, 0xffff0000, v84
	v_pk_mul_f32 v[6:7], v[18:19], v[18:19]
	v_lshlrev_b32_e32 v11, 16, v84
	v_add_f32_e32 v7, v7, v12
	v_add_f32_e32 v12, v6, v7
	v_and_b32_e32 v6, 0xffff0000, v8
	v_lshlrev_b32_e32 v7, 16, v8
	v_pk_fma_f32 v[16:17], v[148:149], v[10:11], v[6:7] neg_lo:[1,0,0] neg_hi:[1,0,0]
	v_and_b32_e32 v8, 0xffff0000, v85
	v_pk_mul_f32 v[6:7], v[16:17], v[16:17]
	s_nop 0
	v_add_f32_e32 v7, v7, v12
	v_add_f32_e32 v10, v6, v7
	v_and_b32_e32 v6, 0xffff0000, v9
	v_lshlrev_b32_e32 v7, 16, v9
	v_lshlrev_b32_e32 v9, 16, v85
	v_pk_fma_f32 v[14:15], v[148:149], v[8:9], v[6:7] neg_lo:[1,0,0] neg_hi:[1,0,0]
	s_nop 0
	v_pk_mul_f32 v[6:7], v[14:15], v[14:15]
	s_nop 0
	v_add_f32_e32 v7, v7, v10
	v_add_f32_e32 v6, v6, v7
	ds_swizzle_b32 v7, v6 offset:swizzle(SWAP,1)
	s_waitcnt lgkmcnt(0)
;     DI void* gp(int i) const { return (void*)(__attribute__((address_space(1))) void*)ld(i); }
; DI unsigned cvtpk(float lo, float hi) { unsigned r; asm volatile("v_cvt_pk_bf16_f32 %0, %1, %2" : "=v"(r) : "v"(lo), "v"(hi)); return r; }
; template <int DQK, int MODE>
; DI void attn_body(const AttnArgs& a, char* lds) {
;     ...
;             const float rn = rsqrtf(ss * (1.f / 128.f) + EPS) * a.oscale;
;             const float* gg = a.ga + hf * 64;
; #pragma unroll
;             for (int c = 0; c < 8; ++c) { const f32x4 g0 = *(const f32x4*)(gg + c * 8), g1 = *(const f32x4*)(gg + c * 8 + 4);
;                 u32x4 w; w.x = cvtpk(v[c * 8] * rn * g0[0], v[c * 8 + 1] * rn * g0[1]); w.y = cvtpk(v[c * 8 + 2] * rn * g0[2], v[c * 8 + 3] * rn * g0[3]);
;                 w.z = cvtpk(v[c * 8 + 4] * rn * g1[0], v[c * 8 + 5] * rn * g1[1]); w.w = cvtpk(v[c * 8 + 6] * rn * g1[2], v[c * 8 + 7] * rn * g1[3]);
;                 *(u32x4*)(gp + c * 8) = w; }
	v_add_f32_e32 v6, v6, v7
	v_fmamk_f32 v6, v6, 0x3c000000, v185
	v_cmp_gt_f32_e32 vcc, s95, v6
	v_mul_f32_e32 v7, 0x4b800000, v6
	s_nop 0
	v_cndmask_b32_e32 v6, v6, v7, vcc
	v_rsq_f32_e32 v6, v6
	s_nop 0
	v_mul_f32_e32 v7, 0x45800000, v6
	v_cndmask_b32_e32 v6, v6, v7, vcc
	v_mul_f32_e32 v69, v156, v6
	v_mul_f32_e32 v29, v29, v69
	v_mul_f32_e32 v21, v21, v69
	v_mul_f32_e32 v20, v20, v69
	v_mul_f32_e32 v10, v86, v29
	v_mul_f32_e32 v29, v31, v69
	v_mul_f32_e32 v11, v87, v29
	v_cvt_pk_bf16_f32 v10, v10, v11
	v_mul_f32_e32 v11, v34, v69
	v_mul_f32_e32 v11, v88, v11
	v_mul_f32_e32 v12, v37, v69
	v_mul_f32_e32 v12, v89, v12
	v_cvt_pk_bf16_f32 v11, v11, v12
	v_mul_f32_e32 v12, v39, v69
	v_mul_f32_e32 v6, v90, v12
	v_mul_f32_e32 v12, v41, v69
	v_mul_f32_e32 v7, v91, v12
	v_cvt_pk_bf16_f32 v12, v6, v7
	v_mul_f32_e32 v6, v50, v69
	v_mul_f32_e32 v7, v56, v69
	v_mul_f32_e32 v6, v92, v6
	v_mul_f32_e32 v7, v93, v7
	v_cvt_pk_bf16_f32 v13, v6, v7
	global_store_dwordx4 v[26:27], v[10:13], off
	s_nop 1
	v_mul_f32_e32 v29, v51, v69
	v_mul_f32_e32 v10, v94, v29
	v_mul_f32_e32 v29, v52, v69
	v_mul_f32_e32 v11, v95, v29
	v_cvt_pk_bf16_f32 v10, v10, v11
	v_mul_f32_e32 v11, v53, v69
	v_mul_f32_e32 v11, v96, v11
	v_mul_f32_e32 v12, v54, v69
	v_mul_f32_e32 v12, v97, v12
	v_cvt_pk_bf16_f32 v11, v11, v12
	v_mul_f32_e32 v12, v55, v69
	v_mul_f32_e32 v6, v98, v12
	v_mul_f32_e32 v12, v57, v69
	v_mul_f32_e32 v7, v99, v12
	v_cvt_pk_bf16_f32 v12, v6, v7
	v_mul_f32_e32 v6, v58, v69
	v_mul_f32_e32 v7, v59, v69
	v_mul_f32_e32 v6, v100, v6
	v_mul_f32_e32 v7, v101, v7
	v_cvt_pk_bf16_f32 v13, v6, v7
	global_store_dwordx4 v[26:27], v[10:13], off offset:16
	s_nop 1
	v_mul_f32_e32 v29, v42, v69
	v_mul_f32_e32 v10, v102, v29
	v_mul_f32_e32 v29, v43, v69
	v_mul_f32_e32 v11, v103, v29
	v_cvt_pk_bf16_f32 v10, v10, v11
	v_mul_f32_e32 v11, v44, v69
	v_mul_f32_e32 v11, v104, v11
	v_mul_f32_e32 v12, v45, v69
	v_mul_f32_e32 v12, v105, v12
	v_cvt_pk_bf16_f32 v11, v11, v12
	v_mul_f32_e32 v12, v46, v69
	v_mul_f32_e32 v6, v106, v12
	v_mul_f32_e32 v12, v47, v69
	v_mul_f32_e32 v7, v107, v12
	v_cvt_pk_bf16_f32 v12, v6, v7
	v_mul_f32_e32 v6, v48, v69
	v_mul_f32_e32 v7, v49, v69
	v_mul_f32_e32 v6, v108, v6
	v_mul_f32_e32 v7, v109, v7
	v_cvt_pk_bf16_f32 v13, v6, v7
	global_store_dwordx4 v[26:27], v[10:13], off offset:32
	s_nop 1
	v_mul_f32_e32 v29, v40, v69
	v_mul_f32_e32 v10, v110, v29
	v_mul_f32_e32 v29, v38, v69
	v_mul_f32_e32 v11, v111, v29
	v_cvt_pk_bf16_f32 v10, v10, v11
	v_mul_f32_e32 v11, v36, v69
	v_mul_f32_e32 v11, v112, v11
	v_mul_f32_e32 v12, v35, v69
	v_mul_f32_e32 v12, v113, v12
	v_cvt_pk_bf16_f32 v11, v11, v12
	v_mul_f32_e32 v12, v33, v69
	v_mul_f32_e32 v6, v114, v12
	v_mul_f32_e32 v12, v32, v69
	v_mul_f32_e32 v7, v115, v12
	v_cvt_pk_bf16_f32 v12, v6, v7
	v_mul_f32_e32 v6, v30, v69
	v_mul_f32_e32 v7, v28, v69
	v_mul_f32_e32 v6, v116, v6
	v_mul_f32_e32 v7, v117, v7
	v_cvt_pk_bf16_f32 v13, v6, v7
	global_store_dwordx4 v[26:27], v[10:13], off offset:48
	s_nop 1
	v_mul_f32_e32 v28, v81, v69
	v_mul_f32_e32 v10, v118, v28
	v_mul_f32_e32 v28, v80, v69
	v_mul_f32_e32 v11, v119, v28
	v_cvt_pk_bf16_f32 v10, v10, v11
	v_mul_f32_e32 v11, v79, v69
	v_mul_f32_e32 v11, v120, v11
	v_mul_f32_e32 v12, v78, v69
	v_mul_f32_e32 v12, v121, v12
	v_cvt_pk_bf16_f32 v11, v11, v12
	v_mul_f32_e32 v12, v75, v69
	v_mul_f32_e32 v6, v122, v12
	v_mul_f32_e32 v12, v74, v69
	v_mul_f32_e32 v7, v123, v12
	v_cvt_pk_bf16_f32 v12, v6, v7
	v_mul_f32_e32 v6, v71, v69
	v_mul_f32_e32 v7, v70, v69
	v_mul_f32_e32 v6, v124, v6
	v_mul_f32_e32 v7, v125, v7
	v_cvt_pk_bf16_f32 v13, v6, v7
	global_store_dwordx4 v[26:27], v[10:13], off offset:64
	s_nop 1
	v_mul_f32_e32 v28, v66, v69
	v_mul_f32_e32 v10, v126, v28
	v_mul_f32_e32 v28, v65, v69
	v_mul_f32_e32 v11, v127, v28
	v_cvt_pk_bf16_f32 v10, v10, v11
	v_mul_f32_e32 v11, v64, v69
	v_mul_f32_e32 v11, v128, v11
	v_mul_f32_e32 v12, v63, v69
	v_mul_f32_e32 v12, v129, v12
	v_cvt_pk_bf16_f32 v11, v11, v12
	v_mul_f32_e32 v12, v62, v69
	v_mul_f32_e32 v6, v130, v12
	v_mul_f32_e32 v12, v61, v69
	v_mul_f32_e32 v7, v131, v12
	v_cvt_pk_bf16_f32 v12, v6, v7
	v_mul_f32_e32 v6, v25, v69
	v_mul_f32_e32 v7, v24, v69
	v_mul_f32_e32 v6, v132, v6
	v_mul_f32_e32 v7, v133, v7
	v_cvt_pk_bf16_f32 v13, v6, v7
	global_store_dwordx4 v[26:27], v[10:13], off offset:80
	s_nop 1
	v_mul_f32_e32 v24, v77, v69
	v_mul_f32_e32 v10, v134, v24
	v_mul_f32_e32 v24, v76, v69
	v_mul_f32_e32 v11, v135, v24
	v_cvt_pk_bf16_f32 v10, v10, v11
	v_mul_f32_e32 v11, v73, v69
	v_mul_f32_e32 v11, v136, v11
	v_mul_f32_e32 v12, v72, v69
	v_mul_f32_e32 v12, v137, v12
	v_cvt_pk_bf16_f32 v11, v11, v12
	v_mul_f32_e32 v12, v68, v69
	v_mul_f32_e32 v6, v138, v12
	v_mul_f32_e32 v12, v67, v69
	v_mul_f32_e32 v7, v139, v12
	v_cvt_pk_bf16_f32 v12, v6, v7
	v_mul_f32_e32 v6, v23, v69
	v_mul_f32_e32 v7, v22, v69
	v_mul_f32_e32 v6, v140, v6
	v_mul_f32_e32 v7, v141, v7
	v_cvt_pk_bf16_f32 v13, v6, v7
	global_store_dwordx4 v[26:27], v[10:13], off offset:96
	s_nop 1
	v_mul_f32_e32 v10, v142, v21
	v_mul_f32_e32 v11, v143, v20
	v_cvt_pk_bf16_f32 v10, v10, v11
	v_mul_f32_e32 v11, v19, v69
	v_mul_f32_e32 v11, v144, v11
	v_mul_f32_e32 v12, v18, v69
	v_mul_f32_e32 v12, v145, v12
	v_cvt_pk_bf16_f32 v11, v11, v12
	v_mul_f32_e32 v12, v17, v69
	v_mul_f32_e32 v6, v194, v12
	v_mul_f32_e32 v12, v16, v69
	v_mul_f32_e32 v7, v195, v12
	v_cvt_pk_bf16_f32 v12, v6, v7
	v_mul_f32_e32 v6, v15, v69
	v_mul_f32_e32 v7, v14, v69
	v_mul_f32_e32 v6, v196, v6
	v_mul_f32_e32 v7, v197, v7
	v_cvt_pk_bf16_f32 v13, v6, v7
	global_store_dwordx4 v[26:27], v[10:13], off offset:112
	s_nop 1
	s_cbranch_execnz .LBB0_736
